# attnA loop: next-tile K/V loads use scalar base + invariant lane offset (SALU pointer arithmetic), staging write addresses hoisted
# speedup vs baseline: 1.0065x; 1.0019x over previous
; DI int ltid_w(int wave) { int t; asm volatile("v_mbcnt_lo_u32_b32 %0, -1, 0\n\tv_mbcnt_hi_u32_b32 %0, -1, %0" : "=v"(t)); return (wave << 6) | t; }
; template <int MODE>
; DI void attn_mfma(const Params& p, int l, int b, int hd, int qb, unsigned char* smem) {
;     ...
;   const int tid = ltid_w(p.wave), lane = tid & 63, wv = tid >> 6, r = lane & 31, h2 = lane >> 5;
;   const int mp = MODE ? 0 : (wv >> 1);
;   const bf16_t* P = (const bf16_t*)(p.ws + WS_P);
;   bf16_t* MIX = (bf16_t*)(p.ws + WS_HM);
;   const int kvh = MODE ? (hd >> 1) : hd;
;   const bf16_t* VT = MODE ? (const bf16_t*)(p.ws + WS_VTC) + ((size_t)(b * 2 + kvh) * 64) * NTOK : (const bf16_t*)(p.ws + WS_VTA) + ((size_t)(b * 4 + hd) * 64) * NTOK;
;   const int qcol = MODE ? C_Q + hd * 64 : A_Q + hd * 64;
;   const int kcol = MODE ? C_K + kvh * 64 : A_K + hd * 64;
;   unsigned char* sK = smem;
;   unsigned char* sV = smem + 8192;
;   const int tq = qb * QPB + (MODE ? wv : (wv & 1)) * 32 + r;
;   const size_t qrow = (size_t)b * NTOK + tq;
;   bf16x8 qf[KS];
; #pragma unroll
;   for (int ks = 0; ks < KS; ++ks) qf[ks] = *(const bf16x8*)(P + qrow * PW + qcol + (2 * (mp * 2 + ks) + h2) * 8);
;   const bool isctx = qb * QPB < NCTX;
;   int ntiles, band_lo = 0;
;   if (MODE == 0) ntiles = isctx ? 4 : 36;
;   else {
;     if (isctx) ntiles = 4;
;     else { const int i0 = qb * QPB - NCTX; int lo = i0 - 128; if (lo < 0) lo = 0; int hi = i0 + 256; if (hi > NLAT) hi = NLAT; band_lo = lo; ntiles = 4 + (hi - lo) / 64; }
;   }
;   const float cexp = (MODE ? 0.125f : 0.17677669529663687f) * 1.4426950408889634f;
;   float mrun = MODE ? p.sw_sink[l * 4 + hd] * 1.4426950408889634f : -1e30f;
;   float lsum = (MODE && h2 == 0) ? 1.f : 0.f;
;   f32x16 O[2];
; #pragma unroll
;   for (int vt = 0; vt < 2; ++vt)
; #pragma unroll
;     for (int i = 0; i < 16; ++i) O[vt][i] = 0.f;
;   const int lrow = tid >> 3, lc = tid & 7;
;   auto tile_base = [&](int j) -> int { return (MODE == 0 || j < 4) ? j * 64 : NCTX + band_lo + (j - 4) * 64; };
;   uint4 gk00, gk01, gk10, gk11, gv00, gv01, gv10, gv11;
;     ...
;   ATT_LOAD(tile_base(0), gk00, gk01, gv00, gv01);
;   ATT_LOAD(tile_base(1), gk10, gk11, gv10, gv11);
.LBB0_575:
	s_andn2_b64 vcc, exec, s[0:1]
	s_cbranch_vccnz .LBB0_591
	s_add_i32 s0, s46, 0xffc0
	s_and_b32 s8, s0, 0xffff
	s_mul_i32 s1, s8, 0xe38f
	s_lshr_b32 s5, s1, 21
	s_mul_i32 s1, s5, 36
	s_sub_i32 s2, s0, s1
	s_and_b32 s0, s2, 0xffff
	s_cmp_lt_u32 s0, 4
	v_readlane_b32 s6, v254, 12
	s_cselect_b64 s[0:1], -1, 0
	v_readlane_b32 s7, v254, 13
	s_and_b64 s[6:7], s[6:7], s[0:1]
	s_and_b64 vcc, exec, s[6:7]
	s_cbranch_vccnz .LBB0_591
	s_and_b32 s4, 0xffff, s5
	s_lshr_b32 s9, s4, 2
	s_and_b32 s6, s4, 3
	v_readlane_b32 s4, v253, 39
	s_add_u32 s10, s40, 0x41c6000
	v_mbcnt_lo_u32_b32 v6, -1, 0
	v_mbcnt_hi_u32_b32 v6, -1, v6
	s_addc_u32 s11, s41, 0
	v_or_b32_e32 v196, s4, v6
	s_lshl_b32 s4, s9, 8
	s_lshl_b32 s7, s6, 6
	s_or_b32 s4, s7, s4
	s_mulk_i32 s4, 0x1200
	s_add_u32 s4, s40, s4
	s_addc_u32 s13, s41, 0
	s_add_u32 s12, s4, 0xef06000
	s_addc_u32 s13, s13, 0
	s_lshl_b32 s2, s2, 6
	s_and_b32 s2, s2, 0xffc0
	v_lshrrev_b32_e32 v0, 1, v196
	s_mul_i32 s14, s9, 0x900
	v_and_b32_e32 v198, 31, v6
	v_and_b32_e32 v199, 32, v0
	s_add_i32 s2, s14, s2
	v_bfe_u32 v171, v6, 5, 1
	v_or3_b32 v165, v198, s2, v199
	v_ashrrev_i32_e32 v197, 7, v196
	v_mul_lo_u32 v160, v165, s33
	v_lshlrev_b32_e32 v164, 3, v171
	v_lshl_add_u64 v[166:167], s[10:11], 0, v[160:161]
	s_lshl_b32 s2, s6, 7
	v_lshl_or_b32 v2, v197, 5, v164
	v_lshl_add_u64 v[0:1], v[166:167], 0, s[2:3]
	v_ashrrev_i32_e32 v3, 31, v2
	v_lshl_add_u64 v[0:1], v[2:3], 1, v[0:1]
	v_ashrrev_i32_e32 v8, 3, v196
	s_waitcnt vmcnt(0)
	global_load_dwordx4 v[96:99], v[0:1], off
	global_load_dwordx4 v[100:103], v[0:1], off offset:32
	v_add_u32_e32 v7, s14, v8
	v_mov_b64_e32 v[0:1], s[10:11]
	v_lshlrev_b32_e32 v9, 4, v6
	s_and_b64 s[0:1], s[0:1], exec
	v_mad_i64_i32 v[2:3], s[0:1], v7, s33, v[0:1]
	v_and_b32_e32 v160, 0x70, v9
	s_cselect_b32 s4, 4, 36
	v_lshl_add_u64 v[4:5], v[2:3], 0, s[2:3]
	v_lshl_add_u64 v[2:3], v[2:3], 0, v[160:161]
	s_or_b32 s0, s2, 0x200
	s_mov_b32 s1, s3
	v_lshl_add_u64 v[2:3], v[2:3], 0, s[0:1]
	s_mov_b32 s14, 0x44000
	v_add_co_u32_e32 v2, vcc, s14, v2
	v_lshl_add_u64 v[4:5], v[4:5], 0, v[160:161]
	s_nop 0
	v_addc_co_u32_e32 v3, vcc, 0, v3, vcc
	global_load_dwordx4 v[104:107], v[4:5], off offset:512
	global_load_dwordx4 v[108:111], v[2:3], off offset:1024
	v_mov_b64_e32 v[2:3], s[12:13]
	v_add_u32_e32 v6, 32, v8
	v_mad_i64_i32 v[4:5], s[10:11], v8, s67, v[2:3]
	v_mad_i64_i32 v[2:3], s[10:11], v6, s67, v[2:3]
	v_add_u32_e32 v6, 64, v7
	v_mad_i64_i32 v[0:1], s[10:11], v6, s33, v[0:1]
	v_lshl_add_u64 v[6:7], v[0:1], 0, s[2:3]
	v_lshl_add_u64 v[0:1], v[0:1], 0, v[160:161]
	v_lshl_add_u64 v[0:1], v[0:1], 0, s[0:1]
	v_lshl_add_u64 v[6:7], v[6:7], 0, v[160:161]
	v_add_co_u32_e32 v0, vcc, s14, v0
	v_lshl_add_u64 v[4:5], v[4:5], 0, v[160:161]
	v_lshl_add_u64 v[2:3], v[2:3], 0, v[160:161]
	v_addc_co_u32_e32 v1, vcc, 0, v1, vcc
	global_load_dwordx4 v[112:115], v[6:7], off offset:512
	global_load_dwordx4 v[116:119], v[0:1], off offset:1024
	global_load_dwordx4 v[120:123], v[4:5], off
	global_load_dwordx4 v[124:127], v[4:5], off offset:128
	global_load_dwordx4 v[128:131], v[2:3], off
	global_load_dwordx4 v[132:135], v[2:3], off offset:128
	s_movk_i32 s0, 0x70
	v_bitop3_b32 v0, v196, s0, v9 bitop3:0x48
	s_movk_i32 s0, 0x88
	v_mul_lo_u32 v2, v8, s0
	s_mul_i32 s0, s9, 0x90000
	s_mul_i32 s1, s6, 0x24000
	s_add_i32 s0, s0, s1
	v_lshlrev_b32_e32 v1, 2, v197
	v_bfe_u32 v4, v196, 1, 3
	s_lshl_b32 s0, s0, 1
	v_lshl_or_b32 v141, v8, 7, v0
	v_lshlrev_b32_e32 v0, 7, v198
	v_or_b32_e32 v3, v1, v171
	v_bitop3_b32 v1, v1, v4, v171 bitop3:0x36
	s_add_u32 s0, s40, s0
	v_lshl_add_u32 v142, v1, 4, v0
	v_bitop3_b32 v1, v3, v4, 2 bitop3:0x36
	s_addc_u32 s1, s41, 0
	v_lshl_add_u32 v143, v1, 4, v0
	v_mov_b64_e32 v[0:1], s[0:1]
	s_mov_b64 s[12:13], s[0:1]
	s_and_b32 s5, s5, 3
	v_mbcnt_hi_u32_b32 v5, -1, v185
	v_mad_i64_i32 v[136:137], s[0:1], v8, s67, v[0:1]
	s_lshl_b32 s5, s5, 7
	v_and_b32_e32 v7, 64, v5
	s_mul_hi_u32 s0, s8, 0x1c71c72
	s_add_u32 s5, s40, s5
	v_xor_b32_e32 v6, 32, v5
	v_add_u32_e32 v7, 64, v7
	s_mul_hi_u32 s1, s0, 0x1332000
	s_mul_i32 s0, s0, 0x1332000
	s_addc_u32 s8, s41, 0
	v_cmp_lt_i32_e32 vcc, v6, v7
	s_add_u32 s0, s5, s0
	s_addc_u32 s1, s8, s1
	v_cndmask_b32_e32 v5, v5, v6, vcc
	v_lshlrev_b32_e32 v170, 2, v5
	v_mul_u32_u24_e32 v5, 0x88, v198
	v_mov_b64_e32 v[0:1], s[0:1]
	s_mov_b64 s[10:11], s[0:1]
	v_mov_b32_e32 v200, 0
	s_mov_b32 s2, 0
	v_mad_i64_i32 v[138:139], s[0:1], v8, s33, v[0:1]
	v_mov_b32_e32 v140, 0xf149f2ca
	v_add_u32_e32 v144, v2, v160
	v_mul_lo_u32 v156, v8, s33
	v_mul_lo_u32 v157, v8, s67
	v_add_u32_e32 v158, 0x2000, v144
	v_add_u32_e32 v159, 0x3100, v144
	v_add_u32_e32 v201, 0x6200, v144
	v_add_u32_e32 v202, 0x7300, v144
	v_add_u32_e32 v156, v156, v160
	v_add_u32_e32 v157, v157, v160
	v_add_u32_e32 v145, v164, v5
	v_add_u32_e32 v236, 0x2000, v145
	v_add_u32_e32 v237, 0x3000, v145
	v_add_u32_e32 v238, 0x6000, v145
	v_add_u32_e32 v239, 0x7000, v145
	v_mov_b32_e32 v16, 0
	v_mov_b32_e32 v17, v200
	v_mov_b32_e32 v18, v200
	v_mov_b32_e32 v19, v200
	v_mov_b32_e32 v20, v200
	v_mov_b32_e32 v21, v200
	v_mov_b32_e32 v22, v200
	v_mov_b32_e32 v23, v200
	v_mov_b32_e32 v24, v200
	v_mov_b32_e32 v25, v200
	v_mov_b32_e32 v26, v200
	v_mov_b32_e32 v27, v200
	v_mov_b32_e32 v28, v200
	v_mov_b32_e32 v29, v200
	v_mov_b32_e32 v30, v200
	v_mov_b32_e32 v31, v200
	v_mov_b32_e32 v0, v200
	v_mov_b32_e32 v1, v200
	v_mov_b32_e32 v2, v200
	v_mov_b32_e32 v3, v200
	v_mov_b32_e32 v4, v200
	v_mov_b32_e32 v5, v200
	v_mov_b32_e32 v6, v200
	v_mov_b32_e32 v7, v200
	v_mov_b32_e32 v8, v200
	v_mov_b32_e32 v9, v200
	v_mov_b32_e32 v10, v200
	v_mov_b32_e32 v11, v200
	v_mov_b32_e32 v12, v200
	v_mov_b32_e32 v13, v200
	v_mov_b32_e32 v14, v200
	v_mov_b32_e32 v15, v200
	s_branch .LBB0_580
; template <int MODE>
; DI void attn_mfma(const Params& p, int l, int b, int hd, int qb, unsigned char* smem) {
;     ...
;   for (int j = 0; j < ntiles; j += 2) {
;     __syncthreads();
;     ATT_STORE(0, gk00, gk01, gv00, gv01);
;     ATT_STORE(1, gk10, gk11, gv10, gv11);
;     __syncthreads();
;     if (j + 2 < ntiles) {
;       ATT_LOAD(tile_base(j + 2), gk00, gk01, gv00, gv01);
;       ATT_LOAD(tile_base(j + 3), gk10, gk11, gv10, gv11);
;     }
.LBB0_580:
	s_add_i32 s2, s2, 2
	s_waitcnt lgkmcnt(0)
	s_barrier
	s_waitcnt vmcnt(0)
	ds_write_b128 v141, v[104:107]
	ds_write_b128 v141, v[108:111] offset:4096
	ds_write2_b64 v158, v[120:121], v[122:123] offset1:1
	s_cmp_ge_u32 s2, s4
	ds_write2_b64 v159, v[128:129], v[130:131] offset1:1
	ds_write_b128 v141, v[112:115] offset:16896
	ds_write_b128 v141, v[116:119] offset:20992
	s_cselect_b64 s[0:1], -1, 0
	ds_write2_b64 v201, v[124:125], v[126:127] offset1:1
	s_and_b64 vcc, exec, s[0:1]
	ds_write2_b64 v202, v[132:133], v[134:135] offset1:1
	s_waitcnt lgkmcnt(0)
	s_barrier
	ds_read_b128 v[204:207], v142
	ds_read_b128 v[208:211], v143
	ds_read_b128 v[212:215], v142 offset:4096
	ds_read_b128 v[216:219], v143 offset:4096
	ds_read_b128 v[220:223], v142 offset:16896
	ds_read_b128 v[224:227], v143 offset:16896
	ds_read_b128 v[228:231], v142 offset:20992
	ds_read_b128 v[232:235], v143 offset:20992
	s_cbranch_vccnz .LBB0_582
	s_add_u32 s8, s10, 0x42d7000
	s_addc_u32 s9, s11, 0
	global_load_dwordx4 v[104:107], v156, s[8:9] offset:512
	s_add_u32 s8, s10, 0x431b000
	s_addc_u32 s9, s11, 0
	global_load_dwordx4 v[108:111], v156, s[8:9] offset:1536
	s_add_u32 s8, s10, 0x435f000
	s_addc_u32 s9, s11, 0
	global_load_dwordx4 v[112:115], v156, s[8:9] offset:2560
	s_add_u32 s8, s10, 0x43a3000
	s_addc_u32 s9, s11, 0
	global_load_dwordx4 v[116:119], v156, s[8:9] offset:3584
	s_add_u32 s8, s12, 0xef06000
	s_addc_u32 s9, s13, 0
	global_load_dwordx4 v[120:123], v157, s[8:9] offset:256
	global_load_dwordx4 v[124:127], v157, s[8:9] offset:384
	s_add_u32 s8, s12, 0xef2a000
	s_addc_u32 s9, s13, 0
	global_load_dwordx4 v[128:131], v157, s[8:9] offset:256
	global_load_dwordx4 v[132:135], v157, s[8:9] offset:384

; DI unsigned pk2(float a, float b) { hwf32x2 f = {a, b}; hwbf16x2 r = __builtin_convertvector(f, hwbf16x2); return __builtin_bit_cast(unsigned, r); }
; #define MFMA32(a, b, c) __builtin_amdgcn_mfma_f32_32x32x16_bf16((a), (b), (c), 0, 0, 0)
; template <int MODE>
; DI void attn_mfma(const Params& p, int l, int b, int hd, int qb, unsigned char* smem) {
;     ...
;     const f32x2 c2 = {cexp, cexp}, m2 = {mrun, mrun};
;     f32x2 ps2 = {0.f, 0.f};
;     unsigned pk[2][8];
; #pragma unroll
;     for (int mt = 0; mt < 2; ++mt)
; #pragma unroll
;       for (int i = 0; i < 8; ++i) {
;         f32x2 z = {S[mt][2 * i], S[mt][2 * i + 1]};
;         z = z * c2 - m2;
;         f32x2 pv = {__builtin_amdgcn_exp2f(z.x), __builtin_amdgcn_exp2f(z.y)};
;         ps2 = ps2 + pv;
;         pk[mt][i] = pk2(pv.x, pv.y);
;       }
;     lsum += ps2.x + ps2.y;
; #pragma unroll
;     for (int mt = 0; mt < 2; ++mt)
; #pragma unroll
;       for (int s = 0; s < 2; ++s) {
;         const uint4 pu = make_uint4(pk[mt][4 * s], pk[mt][4 * s + 1], pk[mt][4 * s + 2], pk[mt][4 * s + 3]);
;         const bf16x8 pf = __builtin_bit_cast(bf16x8, pu);
; #pragma unroll
;         for (int vt = 0; vt < 2; ++vt) {
;           const unsigned char* bp = sVc + (vt * 32 + r) * 136 + (mt * 32 + 16 * s + 4 * h2) * 2;
;           const uint2 lo = *(const uint2*)(bp);
;           const uint2 hi = *(const uint2*)(bp + 16);
;           const uint4 u = make_uint4(lo.x, lo.y, hi.x, hi.y);
;           O[vt] = MFMA32(__builtin_bit_cast(bf16x8, u), pf, O[vt]);
;         }
;       }
;     }
;   }
.Laa_nrb:
	v_fma_f32 v48, v48, s8, -v140
	v_fma_f32 v49, v49, s8, -v140
	v_fma_f32 v50, v50, s8, -v140
	v_fma_f32 v51, v51, s8, -v140
	v_fma_f32 v52, v52, s8, -v140
	v_fma_f32 v53, v53, s8, -v140
	v_fma_f32 v54, v54, s8, -v140
	v_fma_f32 v55, v55, s8, -v140
	v_exp_f32_e32 v48, v48
	v_exp_f32_e32 v49, v49
	v_exp_f32_e32 v50, v50
	v_exp_f32_e32 v51, v51
	v_exp_f32_e32 v52, v52
	v_exp_f32_e32 v53, v53
	v_exp_f32_e32 v54, v54
	v_exp_f32_e32 v55, v55
	v_add_f32_e64 v148, v48, 0
	v_add_f32_e64 v149, v49, 0
	v_add_f32_e32 v148, v50, v148
	v_add_f32_e32 v149, v51, v149
	v_add_f32_e32 v148, v52, v148
	v_add_f32_e32 v149, v53, v149
	v_add_f32_e32 v148, v54, v148
	v_add_f32_e32 v149, v55, v149
	v_cvt_pk_bf16_f32 v48, v48, v49
	v_cvt_pk_bf16_f32 v49, v50, v51
	v_cvt_pk_bf16_f32 v50, v52, v53
	v_cvt_pk_bf16_f32 v51, v54, v55
	v_fma_f32 v56, v56, s8, -v140
	v_fma_f32 v57, v57, s8, -v140
	v_fma_f32 v58, v58, s8, -v140
	s_waitcnt lgkmcnt(4)
	v_mfma_f32_32x32x16_bf16 v[16:31], v[204:207], v[48:51], v[16:31]
	v_fma_f32 v59, v59, s8, -v140
	v_fma_f32 v60, v60, s8, -v140
	v_fma_f32 v61, v61, s8, -v140
	v_fma_f32 v62, v62, s8, -v140
	v_fma_f32 v63, v63, s8, -v140
	v_exp_f32_e32 v56, v56
	v_exp_f32_e32 v57, v57
	v_exp_f32_e32 v58, v58
	v_exp_f32_e32 v59, v59
	v_exp_f32_e32 v60, v60
	v_exp_f32_e32 v61, v61
	v_exp_f32_e32 v62, v62
	v_mfma_f32_32x32x16_bf16 v[0:15], v[208:211], v[48:51], v[0:15]
	v_exp_f32_e32 v63, v63
	v_add_f32_e32 v148, v56, v148
	v_add_f32_e32 v149, v57, v149
	v_add_f32_e32 v148, v58, v148
	v_add_f32_e32 v149, v59, v149
	v_add_f32_e32 v148, v60, v148
	v_add_f32_e32 v149, v61, v149
	v_add_f32_e32 v148, v62, v148
	v_add_f32_e32 v149, v63, v149
	v_cvt_pk_bf16_f32 v56, v56, v57
	v_cvt_pk_bf16_f32 v57, v58, v59
	v_cvt_pk_bf16_f32 v58, v60, v61
	v_cvt_pk_bf16_f32 v59, v62, v63
	v_fma_f32 v32, v32, s8, -v140
	v_fma_f32 v33, v33, s8, -v140
	v_fma_f32 v34, v34, s8, -v140
	v_mfma_f32_32x32x16_bf16 v[16:31], v[212:215], v[56:59], v[16:31]
	v_fma_f32 v35, v35, s8, -v140
	v_fma_f32 v36, v36, s8, -v140
	v_fma_f32 v37, v37, s8, -v140
	v_fma_f32 v38, v38, s8, -v140
	v_fma_f32 v39, v39, s8, -v140
	v_exp_f32_e32 v32, v32
	v_exp_f32_e32 v33, v33
	v_exp_f32_e32 v34, v34
	v_exp_f32_e32 v35, v35
	v_exp_f32_e32 v36, v36
	v_exp_f32_e32 v37, v37
	v_exp_f32_e32 v38, v38
	v_mfma_f32_32x32x16_bf16 v[0:15], v[216:219], v[56:59], v[0:15]
	v_exp_f32_e32 v39, v39
	v_add_f32_e32 v148, v32, v148
	v_add_f32_e32 v149, v33, v149
	v_add_f32_e32 v148, v34, v148
	v_add_f32_e32 v149, v35, v149
	v_add_f32_e32 v148, v36, v148
	v_add_f32_e32 v149, v37, v149
	v_add_f32_e32 v148, v38, v148
	v_add_f32_e32 v149, v39, v149
	v_cvt_pk_bf16_f32 v52, v32, v33
	v_cvt_pk_bf16_f32 v53, v34, v35
	v_cvt_pk_bf16_f32 v54, v36, v37
	v_cvt_pk_bf16_f32 v55, v38, v39
	v_fma_f32 v40, v40, s8, -v140
	v_fma_f32 v41, v41, s8, -v140
	v_fma_f32 v42, v42, s8, -v140
	s_waitcnt lgkmcnt(0)
	v_mfma_f32_32x32x16_bf16 v[16:31], v[220:223], v[52:55], v[16:31]
	v_fma_f32 v43, v43, s8, -v140
	v_fma_f32 v44, v44, s8, -v140
	v_fma_f32 v45, v45, s8, -v140
	v_fma_f32 v46, v46, s8, -v140
	v_fma_f32 v47, v47, s8, -v140
	v_exp_f32_e32 v40, v40
	v_exp_f32_e32 v41, v41
	v_exp_f32_e32 v42, v42
	v_exp_f32_e32 v43, v43
	v_exp_f32_e32 v44, v44
	v_exp_f32_e32 v45, v45
	v_exp_f32_e32 v46, v46
	v_mfma_f32_32x32x16_bf16 v[0:15], v[224:227], v[52:55], v[0:15]
	v_exp_f32_e32 v47, v47
	v_add_f32_e32 v148, v40, v148
	v_add_f32_e32 v149, v41, v149
	v_add_f32_e32 v148, v42, v148
	v_add_f32_e32 v149, v43, v149
	v_add_f32_e32 v148, v44, v148
	v_add_f32_e32 v149, v45, v149
	v_add_f32_e32 v148, v46, v148
	v_add_f32_e32 v149, v47, v149
	v_cvt_pk_bf16_f32 v32, v40, v41
	v_cvt_pk_bf16_f32 v33, v42, v43
	v_cvt_pk_bf16_f32 v34, v44, v45
	v_cvt_pk_bf16_f32 v35, v46, v47
	v_add_f32_e32 v151, v148, v149
	v_add_f32_e32 v200, v152, v151
	v_mfma_f32_32x32x16_bf16 v[16:31], v[228:231], v[32:35], v[16:31]
	s_add_u32 s12, s12, 0x100
	s_addc_u32 s13, s13, 0
	s_add_u32 s10, s10, 0x111000
	s_addc_u32 s11, s11, 0
	v_mfma_f32_32x32x16_bf16 v[0:15], v[232:235], v[32:35], v[0:15]
	s_and_b64 vcc, exec, s[0:1]
	s_cbranch_vccz .LBB0_580
